# wbl2 skip when one XCC + 64-bit accumulator zeroing + counted vmcnt(4) at the SwiGLU epilogue row-sum consume
# speedup vs baseline: 1.0134x; 1.0118x over previous
; template <class Epi, class Sched>
; __device__ __forceinline__ void gemm_phase(PG8_LAS unsigned char* lds, const Gemm g, const Sched& S, const Epi& E) {
;     ...
; #pragma unroll
;     for (int a = 0; a < 2; ++a)
; #pragma unroll
;         for (int b = 0; b < 2; ++b)
; #pragma unroll
;             for (int m = 0; m < 4; ++m)
; #pragma unroll
;                 for (int n = 0; n < 2; ++n) acc[a][b][m][n] = (f32x4){0.f, 0.f, 0.f, 0.f};
;     ...
;         const bool has_next = S.next(ui + 1, nxt);
;         const char* nA = has_next ? (const char*)g.A + (size_t)nxt.pm * tstepA : cA; const char* nB = has_next ? (const char*)g.Bt + (size_t)nxt.pn * tstepB : cB;
;         for (int t = 0; t < nt; t += 2) {
;             const bool last = (t == nt - 2);
;             const char* a1 = cA + (size_t)(t + 1) * kstep;
;             const char* a2 = last ? nA : cA + (size_t)(t + 2) * kstep; const char* b2 = last ? nB : cB + (size_t)(t + 2) * kstep;
;             const char* a3 = a2 + kstep; const char* b3 = b2 + kstep;
.LBB0_161:
	s_ashr_i32 s17, s16, 31
	s_lshl_b64 s[18:19], s[16:17], 19
	s_add_u32 s18, s36, s18
	s_addc_u32 s19, s37, s19
	s_and_b64 s[20:21], s[4:5], exec
	s_cselect_b32 s33, s19, s23
	s_cselect_b32 s61, s18, s22
	s_ashr_i32 s15, s14, 31
	s_lshl_b64 s[20:21], s[14:15], 19
	v_readlane_b32 s15, v254, 56
	s_add_u32 s20, s15, s20
	v_readlane_b32 s15, v254, 57
	s_addc_u32 s21, s15, s21
	s_and_b64 s[26:27], s[4:5], exec
	s_cselect_b32 s15, s21, s25
	s_cselect_b32 s70, s20, s24
	s_add_u32 s22, s22, 0x40080
	s_addc_u32 s23, s23, 0
	s_add_u32 s71, s24, 0x100
	v_mov_b32_e32 v2, 0
	s_addc_u32 s75, s25, 0
	s_mov_b32 s64, -2
	v_mov_b32_e32 v3, v2
	v_mov_b32_e32 v4, v2
	v_mov_b32_e32 v5, v2
	v_mov_b32_e32 v6, v2
	v_mov_b32_e32 v7, v2
	v_mov_b32_e32 v8, v2
	v_mov_b32_e32 v9, v2
	v_mov_b32_e32 v18, v2
	v_mov_b32_e32 v19, v2
	s_waitcnt vmcnt(0)
	v_mov_b64_e32 v[20:21], 0
	v_mov_b64_e32 v[22:23], 0
	v_mov_b64_e32 v[24:25], 0
	v_mov_b64_e32 v[34:35], 0
	v_mov_b64_e32 v[36:37], 0
	v_mov_b64_e32 v[38:39], 0
	v_mov_b64_e32 v[40:41], 0
	v_mov_b64_e32 v[50:51], 0
	v_mov_b64_e32 v[52:53], 0
	v_mov_b64_e32 v[54:55], 0
	v_mov_b64_e32 v[56:57], 0
	v_mov_b64_e32 v[10:11], 0
	v_mov_b64_e32 v[12:13], 0
	v_mov_b64_e32 v[14:15], 0
	v_mov_b64_e32 v[16:17], 0
	v_mov_b64_e32 v[26:27], 0
	v_mov_b64_e32 v[28:29], 0
	v_mov_b64_e32 v[30:31], 0
	v_mov_b64_e32 v[32:33], 0
	v_mov_b64_e32 v[42:43], 0
	v_mov_b64_e32 v[44:45], 0
	v_mov_b64_e32 v[46:47], 0
	v_mov_b64_e32 v[48:49], 0
	v_mov_b64_e32 v[58:59], 0
	v_mov_b64_e32 v[60:61], 0
	v_mov_b64_e32 v[62:63], 0
	v_mov_b64_e32 v[64:65], 0
	v_mov_b64_e32 v[66:67], 0
	v_mov_b64_e32 v[68:69], 0
	v_mov_b64_e32 v[70:71], 0
	v_mov_b64_e32 v[72:73], 0
	v_mov_b64_e32 v[82:83], 0
	v_mov_b64_e32 v[84:85], 0
	v_mov_b64_e32 v[86:87], 0
	v_mov_b64_e32 v[88:89], 0
	v_mov_b64_e32 v[98:99], 0
	v_mov_b64_e32 v[100:101], 0
	v_mov_b64_e32 v[102:103], 0
	v_mov_b64_e32 v[104:105], 0
	v_mov_b64_e32 v[114:115], 0
	v_mov_b64_e32 v[116:117], 0
	v_mov_b64_e32 v[118:119], 0
	v_mov_b64_e32 v[120:121], 0
	v_mov_b64_e32 v[74:75], 0
	v_mov_b64_e32 v[76:77], 0
	v_mov_b64_e32 v[78:79], 0
	v_mov_b64_e32 v[80:81], 0
	v_mov_b64_e32 v[90:91], 0
	v_mov_b64_e32 v[92:93], 0
	v_mov_b64_e32 v[94:95], 0
	v_mov_b64_e32 v[96:97], 0
	v_mov_b64_e32 v[106:107], 0
	v_mov_b64_e32 v[108:109], 0
	v_mov_b64_e32 v[110:111], 0
	v_mov_b64_e32 v[112:113], 0
	v_mov_b64_e32 v[126:127], 0
	v_mov_b64_e32 v[128:129], 0
	v_mov_b64_e32 v[130:131], 0
	v_mov_b64_e32 v[132:133], 0

; #define PG8_STAGE(bufoff, gbase, voff) do { _Pragma("unroll") for (int _i = 0; _i < 2; ++_i) \
;         __builtin_amdgcn_global_load_lds((const unsigned*)((const char*)(gbase) + (voff)[_i]), (PG8_LAS unsigned*)(lds + (bufoff) + ldsw + _i * 8192), 16, 0, 0); } while (0)
; #define PG8_WAIT_V(n) asm volatile("s_waitcnt vmcnt(" #n ")" ::: "memory")
; #define PG8_BAR __builtin_amdgcn_s_barrier()
;     __device__ __forceinline__ void begin(const pg8::Unit& cur, LAS unsigned char* lds, int tid) const { rowstat_begin(rss, cur, lds, tid); }
;     __device__ __forceinline__ void begin(const pg8::Unit& cur, LAS unsigned char* lds, int tid) const { rowstat_begin(rss, cur, lds, tid); }
; template <class Epi, class Sched>
; __device__ __forceinline__ void gemm_phase(PG8_LAS unsigned char* lds, const Gemm g, const Sched& S, const Epi& E) {
;     ...
; #pragma unroll
;     for (int a = 0; a < 2; ++a)
; #pragma unroll
;         for (int b = 0; b < 2; ++b)
; #pragma unroll
;             for (int m = 0; m < 4; ++m)
; #pragma unroll
;                 for (int n = 0; n < 2; ++n) acc[a][b][m][n] = (f32x4){0.f, 0.f, 0.f, 0.f};
;     bf16x8 At[4][2], B0[2][2], B1[2][2];
;     const char* cA = (const char*)g.A + (size_t)cur.pm * tstepA; const char* cB = (const char*)g.Bt + (size_t)cur.pn * tstepB;
;     E.begin(cur, lds, tid);
;     PG8_STAGE(PG8_SB(0, 0), cB, voffB); PG8_STAGE(PG8_SB(0, 1), cB + hstepB, voffB); PG8_STAGE(PG8_SA(0, 0), cA, voffA); PG8_STAGE(PG8_SA(0, 1), cA + hstepA, voffA);
;     if (wr == 1) PG8_BAR;
;     PG8_WAIT_V(2); PG8_BAR;
;     PG8_STAGE(PG8_SB(1, 0), cB + kstep, voffB); PG8_STAGE(PG8_SA(1, 0), cA + kstep, voffA); PG8_STAGE(PG8_SB(1, 1), cB + hstepB + kstep, voffB);
;     PG8_WAIT_V(6); PG8_BAR;
.LBB0_240:
	v_mov_b32_e32 v133, v0
	v_lshl_add_u64 v[10:11], s[86:87], 0, v[132:133]
	v_mov_b32_e32 v137, v0
	v_lshl_add_u64 v[12:13], s[86:87], 0, v[136:137]
	v_mov_b32_e32 v131, v0
	s_add_i32 m0, s12, 0x18000
	v_lshl_add_u64 v[10:11], v[10:11], 0, s[78:79]
	v_lshl_add_u64 v[14:15], s[52:53], 0, v[130:131]
	v_mov_b32_e32 v135, v0
	s_waitcnt vmcnt(2)
	s_barrier
	global_load_lds_dwordx4 v[10:11], off
	v_lshl_add_u64 v[10:11], v[12:13], 0, s[78:79]
	s_add_i32 m0, s12, 0x1a000
	s_add_i32 s33, s12, 0x8000
	v_lshl_add_u64 v[16:17], s[52:53], 0, v[134:135]
	global_load_lds_dwordx4 v[10:11], off
	v_lshl_add_u64 v[10:11], v[14:15], 0, s[78:79]
	s_mov_b32 m0, s33
	s_add_i32 s47, s12, 0xa000
	global_load_lds_dwordx4 v[10:11], off
	v_lshl_add_u64 v[10:11], v[16:17], 0, s[78:79]
	s_mov_b32 m0, s47
	v_and_b32_e32 v18, 15, v1
	global_load_lds_dwordx4 v[10:11], off
	s_add_i32 m0, s12, 0x1c000
	v_lshl_add_u64 v[10:11], s[92:93], 0, v[132:133]
	global_load_lds_dwordx4 v[10:11], off
	v_lshl_add_u64 v[10:11], s[92:93], 0, v[136:137]
	s_add_i32 m0, s12, 0x1e000
	v_and_b32_e32 v19, 48, v1
	global_load_lds_dwordx4 v[10:11], off
	s_and_b32 s46, s0, 3
	v_lshl_or_b32 v142, s1, 6, v18
	v_lshl_or_b32 v18, v18, 6, v19
	v_lshlrev_b32_e32 v19, 2, v1
	s_lshl_b32 s0, s46, 12
	v_and_b32_e32 v19, 32, v19
	v_bitop3_b32 v143, v18, s0, v19 bitop3:0xde
	s_lshl_b32 s0, s1, 13
	v_lshrrev_b32_e32 v10, 1, v2
	v_mul_lo_u32 v2, v4, s35
	s_movk_i32 s4, 0x3000
	v_bitop3_b32 v18, v18, s0, v19 bitop3:0xde
	v_mad_u64_u32 v[10:11], s[0:1], v10, s4, v[2:3]
	v_or_b32_e32 v2, v10, v3
	v_add_lshl_u32 v2, v2, v5, 1
	v_mov_b32_e32 v3, v0
	v_lshl_add_u64 v[138:139], s[72:73], 0, v[2:3]
	v_lshrrev_b32_e32 v3, 1, v6
	v_mul_lo_u32 v2, v8, s35
	v_mad_u64_u32 v[2:3], s[0:1], v3, s4, v[2:3]
	v_or_b32_e32 v2, v2, v7
	s_waitcnt vmcnt(6)
	v_add_lshl_u32 v2, v2, v9, 1
	v_mov_b32_e32 v3, v0
	v_lshl_add_u64 v[140:141], s[72:73], 0, v[2:3]
	v_mov_b32_e32 v2, 0
	s_mov_b32 s48, -2
	s_mov_b64 s[0:1], 0
	v_add_u32_e32 v144, 0, v18
	v_mov_b32_e32 v3, v2
	v_mov_b32_e32 v4, v2
	v_mov_b32_e32 v5, v2
	v_mov_b32_e32 v6, v2
	v_mov_b32_e32 v7, v2
	v_mov_b32_e32 v8, v2
	v_mov_b32_e32 v9, v2
	v_mov_b32_e32 v10, v2
	v_mov_b32_e32 v11, v2
	v_mov_b32_e32 v12, v2
	v_mov_b32_e32 v13, v2
	v_mov_b32_e32 v14, v2
	v_mov_b32_e32 v15, v2
	v_mov_b32_e32 v16, v2
	v_mov_b32_e32 v17, v2
	v_mov_b32_e32 v18, v2
	v_mov_b32_e32 v19, v2
	s_waitcnt vmcnt(0)
	v_mov_b64_e32 v[20:21], 0
	v_mov_b64_e32 v[22:23], 0
	v_mov_b64_e32 v[24:25], 0
	v_mov_b64_e32 v[26:27], 0
	v_mov_b64_e32 v[28:29], 0
	v_mov_b64_e32 v[30:31], 0
	v_mov_b64_e32 v[32:33], 0
	v_mov_b64_e32 v[66:67], 0
	v_mov_b64_e32 v[68:69], 0
	v_mov_b64_e32 v[70:71], 0
	v_mov_b64_e32 v[72:73], 0
	v_mov_b64_e32 v[74:75], 0
	v_mov_b64_e32 v[76:77], 0
	v_mov_b64_e32 v[78:79], 0
	v_mov_b64_e32 v[80:81], 0
	v_mov_b64_e32 v[82:83], 0
	v_mov_b64_e32 v[84:85], 0
	v_mov_b64_e32 v[86:87], 0
	v_mov_b64_e32 v[88:89], 0
	v_mov_b64_e32 v[90:91], 0
	v_mov_b64_e32 v[92:93], 0
	v_mov_b64_e32 v[94:95], 0
	v_mov_b64_e32 v[96:97], 0
	v_mov_b64_e32 v[34:35], 0
	v_mov_b64_e32 v[36:37], 0
	v_mov_b64_e32 v[38:39], 0
	v_mov_b64_e32 v[40:41], 0
	v_mov_b64_e32 v[42:43], 0
	v_mov_b64_e32 v[44:45], 0
	v_mov_b64_e32 v[46:47], 0
	v_mov_b64_e32 v[48:49], 0
	v_mov_b64_e32 v[50:51], 0
	v_mov_b64_e32 v[52:53], 0
	v_mov_b64_e32 v[54:55], 0
	v_mov_b64_e32 v[56:57], 0
	v_mov_b64_e32 v[58:59], 0
	v_mov_b64_e32 v[60:61], 0
	v_mov_b64_e32 v[62:63], 0
	v_mov_b64_e32 v[64:65], 0
	v_mov_b64_e32 v[98:99], 0
	v_mov_b64_e32 v[100:101], 0
	v_mov_b64_e32 v[102:103], 0
	v_mov_b64_e32 v[104:105], 0
	v_mov_b64_e32 v[106:107], 0
	v_mov_b64_e32 v[108:109], 0
	v_mov_b64_e32 v[110:111], 0
	v_mov_b64_e32 v[112:113], 0
	v_mov_b64_e32 v[114:115], 0
	v_mov_b64_e32 v[116:117], 0
	v_mov_b64_e32 v[118:119], 0
	v_mov_b64_e32 v[120:121], 0
	v_mov_b64_e32 v[122:123], 0
	v_mov_b64_e32 v[124:125], 0
	v_mov_b64_e32 v[126:127], 0
	v_mov_b64_e32 v[128:129], 0
	s_barrier

; template <class Epi, class Sched>
; __device__ __forceinline__ void gemm_phase(PG8_LAS unsigned char* lds, const Gemm g, const Sched& S, const Epi& E) {
;     ...
; #pragma unroll
;     for (int a = 0; a < 2; ++a)
; #pragma unroll
;         for (int b = 0; b < 2; ++b)
; #pragma unroll
;             for (int m = 0; m < 4; ++m)
; #pragma unroll
;                 for (int n = 0; n < 2; ++n) acc[a][b][m][n] = (f32x4){0.f, 0.f, 0.f, 0.f};
;     ...
;         const bool has_next = S.next(ui + 1, nxt);
;         const char* nA = has_next ? (const char*)g.A + (size_t)nxt.pm * tstepA : cA; const char* nB = has_next ? (const char*)g.Bt + (size_t)nxt.pn * tstepB : cB;
;         for (int t = 0; t < nt; t += 2) {
;             const bool last = (t == nt - 2);
;             const char* a1 = cA + (size_t)(t + 1) * kstep;
;             const char* a2 = last ? nA : cA + (size_t)(t + 2) * kstep; const char* b2 = last ? nB : cB + (size_t)(t + 2) * kstep;
.LBB0_255:
	s_and_b64 s[12:13], s[6:7], exec
	s_cselect_b32 vcc_lo, s43, s11
	s_cselect_b32 vcc_hi, s42, s10
	s_add_u32 s74, s10, 0x100
	v_mov_b32_e32 v2, 0
	s_addc_u32 s64, s11, 0
	s_mov_b32 s65, -2
	s_mov_b64 s[10:11], 0
	v_mov_b32_e32 v3, v2
	v_mov_b64_e32 v[4:5], 0
	v_mov_b64_e32 v[6:7], 0
	v_mov_b64_e32 v[8:9], 0
	v_mov_b64_e32 v[18:19], 0
	v_mov_b64_e32 v[20:21], 0
	v_mov_b64_e32 v[22:23], 0
	v_mov_b64_e32 v[24:25], 0
	v_mov_b64_e32 v[34:35], 0
	v_mov_b64_e32 v[36:37], 0
	v_mov_b64_e32 v[38:39], 0
	v_mov_b64_e32 v[40:41], 0
	v_mov_b64_e32 v[50:51], 0
	v_mov_b64_e32 v[52:53], 0
	v_mov_b64_e32 v[54:55], 0
	v_mov_b64_e32 v[56:57], 0
	v_mov_b64_e32 v[10:11], 0
	v_mov_b64_e32 v[12:13], 0
	v_mov_b64_e32 v[14:15], 0
	v_mov_b64_e32 v[16:17], 0
	v_mov_b64_e32 v[26:27], 0
	v_mov_b64_e32 v[28:29], 0
	v_mov_b64_e32 v[30:31], 0
	v_mov_b64_e32 v[32:33], 0
	v_mov_b64_e32 v[42:43], 0
	v_mov_b64_e32 v[44:45], 0
	v_mov_b64_e32 v[46:47], 0
	v_mov_b64_e32 v[48:49], 0
	v_mov_b64_e32 v[58:59], 0
	v_mov_b64_e32 v[60:61], 0
	v_mov_b64_e32 v[62:63], 0
	v_mov_b64_e32 v[64:65], 0
	v_mov_b64_e32 v[66:67], 0
	v_mov_b64_e32 v[68:69], 0
	v_mov_b64_e32 v[70:71], 0
	v_mov_b64_e32 v[72:73], 0
	v_mov_b64_e32 v[82:83], 0
	v_mov_b64_e32 v[84:85], 0
	v_mov_b64_e32 v[86:87], 0
	v_mov_b64_e32 v[88:89], 0
	v_mov_b64_e32 v[98:99], 0
	v_mov_b64_e32 v[100:101], 0
	v_mov_b64_e32 v[102:103], 0
	v_mov_b64_e32 v[104:105], 0
	v_mov_b64_e32 v[114:115], 0
	v_mov_b64_e32 v[116:117], 0
	v_mov_b64_e32 v[118:119], 0
	v_mov_b64_e32 v[120:121], 0
	v_mov_b64_e32 v[74:75], 0
	v_mov_b64_e32 v[76:77], 0
	v_mov_b64_e32 v[78:79], 0
	v_mov_b64_e32 v[80:81], 0
	v_mov_b64_e32 v[90:91], 0
	v_mov_b64_e32 v[92:93], 0
	v_mov_b64_e32 v[94:95], 0
	v_mov_b64_e32 v[96:97], 0
	v_mov_b64_e32 v[106:107], 0
	v_mov_b64_e32 v[108:109], 0
	v_mov_b64_e32 v[110:111], 0
	v_mov_b64_e32 v[112:113], 0
	v_mov_b64_e32 v[122:123], 0
	v_mov_b64_e32 v[124:125], 0
	v_mov_b64_e32 v[126:127], 0
	v_mov_b64_e32 v[128:129], 0

; template <class Epi, class Sched>
; __device__ __forceinline__ void gemm_phase(PG8_LAS unsigned char* lds, const Gemm g, const Sched& S, const Epi& E) {
;     ...
; #pragma unroll
;     for (int a = 0; a < 2; ++a)
; #pragma unroll
;         for (int b = 0; b < 2; ++b)
; #pragma unroll
;             for (int m = 0; m < 4; ++m)
; #pragma unroll
;                 for (int n = 0; n < 2; ++n) acc[a][b][m][n] = (f32x4){0.f, 0.f, 0.f, 0.f};
;     ...
;         const bool has_next = S.next(ui + 1, nxt);
;         const char* nA = has_next ? (const char*)g.A + (size_t)nxt.pm * tstepA : cA; const char* nB = has_next ? (const char*)g.Bt + (size_t)nxt.pn * tstepB : cB;
;         for (int t = 0; t < nt; t += 2) {
;             const bool last = (t == nt - 2);
;             const char* a1 = cA + (size_t)(t + 1) * kstep;
;             const char* a2 = last ? nA : cA + (size_t)(t + 2) * kstep; const char* b2 = last ? nB : cB + (size_t)(t + 2) * kstep;
;             const char* a3 = a2 + kstep; const char* b3 = b2 + kstep;
.LBB0_386:
	s_ashr_i32 s15, s14, 31
	s_lshl_b64 s[16:17], s[14:15], 18
	s_add_u32 s16, s4, s16
	s_addc_u32 s17, s5, s17
	s_and_b64 s[18:19], s[0:1], exec
	s_cselect_b32 s15, s17, s21
	s_cselect_b32 s33, s16, s20
	s_ashr_i32 s13, s12, 31
	s_lshl_b64 s[18:19], s[12:13], 18
	s_add_u32 s18, s27, s18
	s_addc_u32 s19, s28, s19
	s_and_b64 s[24:25], s[0:1], exec
	s_cselect_b32 s13, s19, s23
	s_cselect_b32 s48, s18, s22
	s_add_u32 s20, s20, 0x20080
	s_addc_u32 s21, s21, 0
	s_add_u32 s49, s22, 0x100
	v_mov_b32_e32 v2, 0
	s_addc_u32 s57, s23, 0
	s_mov_b32 s58, -2
	v_mov_b32_e32 v3, v2
	v_mov_b32_e32 v4, v2
	v_mov_b32_e32 v5, v2
	v_mov_b32_e32 v6, v2
	v_mov_b32_e32 v7, v2
	v_mov_b32_e32 v8, v2
	v_mov_b32_e32 v9, v2
	v_mov_b32_e32 v18, v2
	v_mov_b32_e32 v19, v2
	s_waitcnt vmcnt(0)
	v_mov_b64_e32 v[20:21], 0
	v_mov_b64_e32 v[22:23], 0
	v_mov_b64_e32 v[24:25], 0
	v_mov_b64_e32 v[46:47], 0
	v_mov_b64_e32 v[48:49], 0
	v_mov_b64_e32 v[50:51], 0
	v_mov_b64_e32 v[52:53], 0
	v_mov_b64_e32 v[78:79], 0
	v_mov_b64_e32 v[80:81], 0
	v_mov_b64_e32 v[82:83], 0
	v_mov_b64_e32 v[84:85], 0
	v_mov_b64_e32 v[10:11], 0
	v_mov_b64_e32 v[12:13], 0
	v_mov_b64_e32 v[14:15], 0
	v_mov_b64_e32 v[16:17], 0
	v_mov_b64_e32 v[26:27], 0
	v_mov_b64_e32 v[28:29], 0
	v_mov_b64_e32 v[30:31], 0
	v_mov_b64_e32 v[32:33], 0
	v_mov_b64_e32 v[66:67], 0
	v_mov_b64_e32 v[68:69], 0
	v_mov_b64_e32 v[74:75], 0
	v_mov_b64_e32 v[76:77], 0
	v_mov_b64_e32 v[94:95], 0
	v_mov_b64_e32 v[96:97], 0
	v_mov_b64_e32 v[98:99], 0
	v_mov_b64_e32 v[100:101], 0
	v_mov_b64_e32 v[106:107], 0
	v_mov_b64_e32 v[108:109], 0
	v_mov_b64_e32 v[110:111], 0
	v_mov_b64_e32 v[112:113], 0
	v_mov_b64_e32 v[130:131], 0
	v_mov_b64_e32 v[132:133], 0
	v_mov_b64_e32 v[134:135], 0
	v_mov_b64_e32 v[136:137], 0
	v_mov_b64_e32 v[154:155], 0
	v_mov_b64_e32 v[156:157], 0
	v_mov_b64_e32 v[158:159], 0
	v_mov_b64_e32 v[160:161], 0
	v_mov_b64_e32 v[178:179], 0
	v_mov_b64_e32 v[180:181], 0
	v_mov_b64_e32 v[182:183], 0
	v_mov_b64_e32 v[184:185], 0
	v_mov_b64_e32 v[118:119], 0
	v_mov_b64_e32 v[120:121], 0
	v_mov_b64_e32 v[122:123], 0
	v_mov_b64_e32 v[124:125], 0
	v_mov_b64_e32 v[142:143], 0
	v_mov_b64_e32 v[144:145], 0
	v_mov_b64_e32 v[146:147], 0
	v_mov_b64_e32 v[148:149], 0
	v_mov_b64_e32 v[166:167], 0
	v_mov_b64_e32 v[168:169], 0
	v_mov_b64_e32 v[170:171], 0
	v_mov_b64_e32 v[172:173], 0
	v_mov_b64_e32 v[194:195], 0
	v_mov_b64_e32 v[196:197], 0
	v_mov_b64_e32 v[198:199], 0
	v_mov_b64_e32 v[200:201], 0

; template <class Epi, class Sched>
; __device__ __forceinline__ void gemm_phase(PG8_LAS unsigned char* lds, const Gemm g, const Sched& S, const Epi& E) {
;     ...
; #pragma unroll
;     for (int a = 0; a < 2; ++a)
; #pragma unroll
;         for (int b = 0; b < 2; ++b)
; #pragma unroll
;             for (int m = 0; m < 4; ++m)
; #pragma unroll
;                 for (int n = 0; n < 2; ++n) acc[a][b][m][n] = (f32x4){0.f, 0.f, 0.f, 0.f};
;     ...
;         const bool has_next = S.next(ui + 1, nxt);
;         const char* nA = has_next ? (const char*)g.A + (size_t)nxt.pm * tstepA : cA; const char* nB = has_next ? (const char*)g.Bt + (size_t)nxt.pn * tstepB : cB;
;         for (int t = 0; t < nt; t += 2) {
;             const bool last = (t == nt - 2);
;             const char* a1 = cA + (size_t)(t + 1) * kstep;
;             const char* a2 = last ? nA : cA + (size_t)(t + 2) * kstep; const char* b2 = last ? nB : cB + (size_t)(t + 2) * kstep;
;             const char* a3 = a2 + kstep; const char* b3 = b2 + kstep;
.LBB0_463:
	s_ashr_i32 s25, s24, 31
	s_lshl_b64 s[26:27], s[24:25], 19
	s_add_u32 s26, s50, s26
	s_addc_u32 s27, s51, s27
	s_and_b64 s[28:29], s[6:7], exec
	s_cselect_b32 s11, s27, s31
	s_cselect_b32 s13, s26, s30
	s_ashr_i32 s23, s22, 31
	s_lshl_b64 s[28:29], s[22:23], 19
	s_add_u32 s28, s61, s28
	s_addc_u32 s29, s85, s29
	s_and_b64 s[46:47], s[6:7], exec
	s_cselect_b32 s21, s29, s71
	s_cselect_b32 s23, s28, s70
	s_add_u32 s30, s30, 0x40080
	s_addc_u32 s31, s31, 0
	s_add_u32 s25, s70, 0x100
	v_mov_b32_e32 v2, 0
	s_addc_u32 s33, s71, 0
	s_mov_b32 s46, -2
	v_mov_b32_e32 v3, v2
	v_mov_b64_e32 v[4:5], 0
	v_mov_b64_e32 v[6:7], 0
	v_mov_b64_e32 v[8:9], 0
	v_mov_b64_e32 v[18:19], 0
	v_mov_b64_e32 v[20:21], 0
	v_mov_b64_e32 v[22:23], 0
	v_mov_b64_e32 v[24:25], 0
	v_mov_b64_e32 v[34:35], 0
	v_mov_b64_e32 v[36:37], 0
	v_mov_b64_e32 v[38:39], 0
	v_mov_b64_e32 v[40:41], 0
	v_mov_b64_e32 v[50:51], 0
	v_mov_b64_e32 v[52:53], 0
	v_mov_b64_e32 v[54:55], 0
	v_mov_b64_e32 v[56:57], 0
	v_mov_b64_e32 v[10:11], 0
	v_mov_b64_e32 v[12:13], 0
	v_mov_b64_e32 v[14:15], 0
	v_mov_b64_e32 v[16:17], 0
	v_mov_b64_e32 v[26:27], 0
	v_mov_b64_e32 v[28:29], 0
	v_mov_b64_e32 v[30:31], 0
	v_mov_b64_e32 v[32:33], 0
	v_mov_b64_e32 v[42:43], 0
	v_mov_b64_e32 v[44:45], 0
	v_mov_b64_e32 v[46:47], 0
	v_mov_b64_e32 v[48:49], 0
	v_mov_b64_e32 v[58:59], 0
	v_mov_b64_e32 v[60:61], 0
	v_mov_b64_e32 v[62:63], 0
	v_mov_b64_e32 v[64:65], 0
	v_mov_b64_e32 v[66:67], 0
	v_mov_b64_e32 v[68:69], 0
	v_mov_b64_e32 v[70:71], 0
	v_mov_b64_e32 v[72:73], 0
	v_mov_b64_e32 v[82:83], 0
	v_mov_b64_e32 v[84:85], 0
	v_mov_b64_e32 v[86:87], 0
	v_mov_b64_e32 v[88:89], 0
	v_mov_b64_e32 v[114:115], 0
	v_mov_b64_e32 v[116:117], 0
	v_mov_b64_e32 v[118:119], 0
	v_mov_b64_e32 v[120:121], 0
	v_mov_b64_e32 v[130:131], 0
	v_mov_b64_e32 v[132:133], 0
	v_mov_b64_e32 v[134:135], 0
	v_mov_b64_e32 v[136:137], 0
	v_mov_b64_e32 v[74:75], 0
	v_mov_b64_e32 v[76:77], 0
	v_mov_b64_e32 v[78:79], 0
	v_mov_b64_e32 v[80:81], 0
	v_mov_b64_e32 v[102:103], 0
	v_mov_b64_e32 v[104:105], 0
	v_mov_b64_e32 v[110:111], 0
	v_mov_b64_e32 v[112:113], 0
	v_mov_b64_e32 v[122:123], 0
	v_mov_b64_e32 v[124:125], 0
	v_mov_b64_e32 v[126:127], 0
	v_mov_b64_e32 v[128:129], 0
	v_mov_b64_e32 v[138:139], 0
	v_mov_b64_e32 v[140:141], 0
	v_mov_b64_e32 v[142:143], 0
	v_mov_b64_e32 v[144:145], 0

; template <class Epi, class Sched>
; __device__ __forceinline__ void gemm_phase(PG8_LAS unsigned char* lds, const Gemm g, const Sched& S, const Epi& E) {
;     ...
; #pragma unroll
;     for (int a = 0; a < 2; ++a)
; #pragma unroll
;         for (int b = 0; b < 2; ++b)
; #pragma unroll
;             for (int m = 0; m < 4; ++m)
; #pragma unroll
;                 for (int n = 0; n < 2; ++n) acc[a][b][m][n] = (f32x4){0.f, 0.f, 0.f, 0.f};
;     ...
;         const bool has_next = S.next(ui + 1, nxt);
;         const char* nA = has_next ? (const char*)g.A + (size_t)nxt.pm * tstepA : cA; const char* nB = has_next ? (const char*)g.Bt + (size_t)nxt.pn * tstepB : cB;
;         for (int t = 0; t < nt; t += 2) {
;             const bool last = (t == nt - 2);
;             const char* a1 = cA + (size_t)(t + 1) * kstep;
;             const char* a2 = last ? nA : cA + (size_t)(t + 2) * kstep; const char* b2 = last ? nB : cB + (size_t)(t + 2) * kstep;
;             const char* a3 = a2 + kstep; const char* b3 = b2 + kstep;
.LBB0_580:
	s_ashr_i32 s11, s10, 31
	s_lshl_b64 s[16:17], s[10:11], 19
	s_add_u32 s16, s36, s16
	s_addc_u32 s17, s37, s17
	s_and_b64 s[18:19], s[20:21], exec
	s_cselect_b32 s33, s17, s23
	s_cselect_b32 s46, s16, s22
	s_ashr_i32 s15, s14, 31
	s_lshl_b64 s[18:19], s[14:15], 19
	s_add_u32 s18, s29, s18
	s_addc_u32 s19, s30, s19
	s_and_b64 s[26:27], s[20:21], exec
	s_cselect_b32 s15, s19, s25
	s_cselect_b32 s47, s18, s24
	s_add_u32 s22, s22, 0x40080
	s_addc_u32 s23, s23, 0
	s_add_u32 s48, s24, 0x100
	v_mov_b32_e32 v2, 0
	s_addc_u32 s49, s25, 0
	s_mov_b32 s57, -2
	v_mov_b32_e32 v3, v2
	v_mov_b64_e32 v[4:5], 0
	v_mov_b64_e32 v[6:7], 0
	v_mov_b64_e32 v[8:9], 0
	v_mov_b64_e32 v[18:19], 0
	v_mov_b64_e32 v[20:21], 0
	v_mov_b64_e32 v[22:23], 0
	v_mov_b64_e32 v[24:25], 0
	v_mov_b64_e32 v[34:35], 0
	v_mov_b64_e32 v[36:37], 0
	v_mov_b64_e32 v[38:39], 0
	v_mov_b64_e32 v[40:41], 0
	v_mov_b64_e32 v[50:51], 0
	v_mov_b64_e32 v[52:53], 0
	v_mov_b64_e32 v[54:55], 0
	v_mov_b64_e32 v[56:57], 0
	v_mov_b64_e32 v[10:11], 0
	v_mov_b64_e32 v[12:13], 0
	v_mov_b64_e32 v[14:15], 0
	v_mov_b64_e32 v[16:17], 0
	v_mov_b64_e32 v[26:27], 0
	v_mov_b64_e32 v[28:29], 0
	v_mov_b64_e32 v[30:31], 0
	v_mov_b64_e32 v[32:33], 0
	v_mov_b64_e32 v[42:43], 0
	v_mov_b64_e32 v[44:45], 0
	v_mov_b64_e32 v[46:47], 0
	v_mov_b64_e32 v[48:49], 0
	v_mov_b64_e32 v[58:59], 0
	v_mov_b64_e32 v[60:61], 0
	v_mov_b64_e32 v[62:63], 0
	v_mov_b64_e32 v[64:65], 0
	v_mov_b64_e32 v[66:67], 0
	v_mov_b64_e32 v[68:69], 0
	v_mov_b64_e32 v[70:71], 0
	v_mov_b64_e32 v[72:73], 0
	v_mov_b64_e32 v[82:83], 0
	v_mov_b64_e32 v[84:85], 0
	v_mov_b64_e32 v[86:87], 0
	v_mov_b64_e32 v[88:89], 0
	v_mov_b64_e32 v[102:103], 0
	v_mov_b64_e32 v[104:105], 0
	v_mov_b64_e32 v[106:107], 0
	v_mov_b64_e32 v[108:109], 0
	v_mov_b64_e32 v[118:119], 0
	v_mov_b64_e32 v[120:121], 0
	v_mov_b64_e32 v[122:123], 0
	v_mov_b64_e32 v[124:125], 0
	v_mov_b64_e32 v[74:75], 0
	v_mov_b64_e32 v[76:77], 0
	v_mov_b64_e32 v[78:79], 0
	v_mov_b64_e32 v[80:81], 0
	v_mov_b64_e32 v[90:91], 0
	v_mov_b64_e32 v[92:93], 0
	v_mov_b64_e32 v[94:95], 0
	v_mov_b64_e32 v[96:97], 0
	v_mov_b64_e32 v[110:111], 0
	v_mov_b64_e32 v[112:113], 0
	v_mov_b64_e32 v[114:115], 0
	v_mov_b64_e32 v[116:117], 0
	v_mov_b64_e32 v[126:127], 0
	v_mov_b64_e32 v[128:129], 0
	v_mov_b64_e32 v[130:131], 0
	v_mov_b64_e32 v[132:133], 0

; __device__ __forceinline__ unsigned cvt_pk_bf16(float lo, float hi) { unsigned r; asm volatile("v_cvt_pk_bf16_f32 %0, %1, %2" : "=v"(r) : "v"(lo), "v"(hi)); return r; }
; #define LAS __attribute__((address_space(3)))
; __device__ __forceinline__ float sigmoid_f(float x) { return __builtin_amdgcn_rcpf(1.0f + __builtin_amdgcn_exp2f(-1.4426950408889634f * x)); }
;     __device__ __forceinline__ void operator()(const f32x4 (&acc)[2][2][4][2], const pg8::Unit& u, int wr, int wc, int fr, int fq, LAS unsigned char* lds, int wid, int lane, const pg8::Unit& nxt, bool has_next, int ui) const {
;         const int row0 = u.pm * 256 + wr * 64 + fr, col = u.pn * 128 + wc * 32 + fq * 8, tid = wid * 64 + lane;
;         const LAS float* R = (const LAS float*)(lds + RS_OFF) + (ui & 1) * 256;
;         const bool pre = has_next && tid < 256; f32x4 qn = (f32x4){1.f, 1.f, 1.f, 1.f};
;         if (pre) qn = *(const f32x4*)(rss + ((size_t)nxt.pm * 256 + tid) * 4);
; #pragma unroll
;         for (int ai = 0; ai < 2; ++ai) {
; #pragma unroll
;             for (int m = 0; m < 4; ++m) {
;                 const int row = row0 + ai * 128 + m * 16; const float r_ = R[wr * 64 + fr + ai * 128 + m * 16];
;                 const f32x4 g0 = acc[ai][0][m][0] * r_, g1 = acc[ai][0][m][1] * r_, u0 = acc[ai][1][m][0] * r_, u1 = acc[ai][1][m][1] * r_;
;                 v4u w;
;                 w.x = cvt_pk_bf16(g0[0] * sigmoid_f(g0[0]) * u0[0], g0[1] * sigmoid_f(g0[1]) * u0[1]); w.y = cvt_pk_bf16(g0[2] * sigmoid_f(g0[2]) * u0[2], g0[3] * sigmoid_f(g0[3]) * u0[3]);
;                 w.z = cvt_pk_bf16(g1[0] * sigmoid_f(g1[0]) * u1[0], g1[1] * sigmoid_f(g1[1]) * u1[1]); w.w = cvt_pk_bf16(g1[2] * sigmoid_f(g1[2]) * u1[2], g1[3] * sigmoid_f(g1[3]) * u1[3]);
;                 *(v4u*)(ACT + (size_t)row * FF + col) = w;
.LBB0_586:
	s_or_b64 exec, exec, s[22:23]
	s_lshl_b32 s11, s82, 8
	s_and_b32 s11, s11, 0x100
	v_lshl_add_u32 v155, s11, 2, v151
	ds_read_b32 v158, v155
	v_lshl_or_b32 v148, s12, 7, v153
	v_lshl_add_u32 v156, s13, 8, v1
	v_ashrrev_i32_e32 v149, 31, v148
	s_waitcnt lgkmcnt(0)
	v_pk_mul_f32 v[130:131], v[130:131], v[158:159] op_sel_hi:[1,0]
	s_nop 0
	v_mul_f32_e32 v157, 0xbfb8aa3b, v130
	v_exp_f32_e32 v157, v157
	v_pk_mul_f32 v[122:123], v[122:123], v[158:159] op_sel_hi:[1,0]
	v_pk_mul_f32 v[132:133], v[132:133], v[158:159] op_sel_hi:[1,0]
	v_pk_mul_f32 v[124:125], v[124:125], v[158:159] op_sel_hi:[1,0]
	v_add_f32_e32 v157, 1.0, v157
	v_rcp_f32_e32 v157, v157
	v_pk_mul_f32 v[126:127], v[126:127], v[158:159] op_sel_hi:[1,0]
	v_pk_mul_f32 v[118:119], v[118:119], v[158:159] op_sel_hi:[1,0]
	v_pk_mul_f32 v[128:129], v[128:129], v[158:159] op_sel_hi:[1,0]
	v_mul_f32_e32 v130, v130, v157
	v_mul_f32_e32 v122, v122, v130
	v_mul_f32_e32 v130, 0xbfb8aa3b, v131
	v_exp_f32_e32 v130, v130
	v_pk_mul_f32 v[120:121], v[120:121], v[158:159] op_sel_hi:[1,0]
	v_add_f32_e32 v130, 1.0, v130
	v_rcp_f32_e32 v130, v130
	s_nop 0
	v_mul_f32_e32 v130, v131, v130
	v_mul_f32_e32 v123, v123, v130
	v_cvt_pk_bf16_f32 v122, v122, v123
	v_mul_f32_e32 v123, 0xbfb8aa3b, v132
	v_exp_f32_e32 v123, v123
	s_nop 0
	v_add_f32_e32 v123, 1.0, v123
	v_rcp_f32_e32 v123, v123
	s_nop 0
	v_mul_f32_e32 v123, v132, v123
	v_mul_f32_e32 v123, v124, v123
	v_mul_f32_e32 v124, 0xbfb8aa3b, v133
	v_exp_f32_e32 v124, v124
	s_nop 0
	v_add_f32_e32 v124, 1.0, v124
	v_rcp_f32_e32 v124, v124
	s_nop 0
	v_mul_f32_e32 v124, v133, v124
	v_mul_f32_e32 v124, v125, v124
	v_cvt_pk_bf16_f32 v123, v123, v124
	v_mul_f32_e32 v124, 0xbfb8aa3b, v126
	v_exp_f32_e32 v124, v124
	s_nop 0
	v_add_f32_e32 v124, 1.0, v124
	v_rcp_f32_e32 v124, v124
	s_nop 0
	v_mul_f32_e32 v124, v126, v124
	v_mul_f32_e32 v118, v118, v124
	v_mul_f32_e32 v124, 0xbfb8aa3b, v127
	v_exp_f32_e32 v124, v124
	s_nop 0
	v_add_f32_e32 v124, 1.0, v124
	v_rcp_f32_e32 v124, v124
	s_nop 0
	v_mul_f32_e32 v124, v127, v124
	v_mul_f32_e32 v119, v119, v124
	v_cvt_pk_bf16_f32 v124, v118, v119
	v_mul_f32_e32 v118, 0xbfb8aa3b, v128
	v_mul_f32_e32 v119, 0xbfb8aa3b, v129
	v_exp_f32_e32 v118, v118
	v_exp_f32_e32 v119, v119
	v_add_f32_e32 v118, 1.0, v118
	v_add_f32_e32 v119, 1.0, v119
	v_rcp_f32_e32 v118, v118
	v_rcp_f32_e32 v119, v119
	v_mul_f32_e32 v118, v128, v118
	v_mul_f32_e32 v119, v129, v119
	v_mul_f32_e32 v118, v120, v118
	v_mul_f32_e32 v119, v121, v119
	v_mov_b64_e32 v[120:121], s[40:41]
	v_cvt_pk_bf16_f32 v125, v118, v119
	v_mad_i64_i32 v[126:127], s[12:13], v156, s55, v[120:121]
	v_lshlrev_b64 v[118:119], 1, v[148:149]
	v_lshl_add_u64 v[126:127], v[126:127], 0, v[118:119]
	global_store_dwordx4 v[126:127], v[122:125], off
	ds_read_b32 v122, v155 offset:64
	s_nop 0
	v_or_b32_e32 v123, 16, v156
	s_waitcnt lgkmcnt(0)
	v_pk_mul_f32 v[114:115], v[114:115], v[122:123] op_sel_hi:[1,0]
	v_pk_mul_f32 v[124:125], v[104:105], v[122:123] op_sel_hi:[1,0]
	v_pk_mul_f32 v[104:105], v[102:103], v[122:123] op_sel_hi:[1,0]
	v_mul_f32_e32 v102, 0xbfb8aa3b, v114
	v_mul_f32_e32 v103, 0xbfb8aa3b, v115
	v_exp_f32_e32 v102, v102
	v_exp_f32_e32 v103, v103
	v_pk_mul_f32 v[106:107], v[106:107], v[122:123] op_sel_hi:[1,0]
	v_pk_mul_f32 v[116:117], v[116:117], v[122:123] op_sel_hi:[1,0]
	v_add_f32_e32 v102, 1.0, v102
	v_add_f32_e32 v103, 1.0, v103
	v_rcp_f32_e32 v102, v102
	v_rcp_f32_e32 v103, v103
	v_pk_mul_f32 v[108:109], v[108:109], v[122:123] op_sel_hi:[1,0]
	v_pk_mul_f32 v[110:111], v[110:111], v[122:123] op_sel_hi:[1,0]
	v_mul_f32_e32 v102, v114, v102
	v_mul_f32_e32 v103, v115, v103
	v_mul_f32_e32 v102, v106, v102
	v_mul_f32_e32 v103, v107, v103
	v_cvt_pk_bf16_f32 v102, v102, v103
	v_mul_f32_e32 v103, 0xbfb8aa3b, v116
	v_mul_f32_e32 v106, 0xbfb8aa3b, v117
	v_exp_f32_e32 v103, v103
	v_exp_f32_e32 v106, v106
	v_pk_mul_f32 v[112:113], v[112:113], v[122:123] op_sel_hi:[1,0]
	v_add_f32_e32 v103, 1.0, v103
	v_add_f32_e32 v106, 1.0, v106
	v_rcp_f32_e32 v103, v103
	v_rcp_f32_e32 v106, v106
	v_mul_f32_e32 v103, v116, v103
	v_mul_f32_e32 v106, v117, v106
	v_mul_f32_e32 v103, v108, v103
	v_mul_f32_e32 v106, v109, v106
	v_cvt_pk_bf16_f32 v103, v103, v106
	v_mul_f32_e32 v106, 0xbfb8aa3b, v110
	v_exp_f32_e32 v106, v106
	s_nop 0
	v_add_f32_e32 v106, 1.0, v106
	v_rcp_f32_e32 v106, v106
	s_nop 0
	v_mul_f32_e32 v106, v110, v106
	v_mul_f32_e32 v104, v104, v106
	v_mul_f32_e32 v106, 0xbfb8aa3b, v111
	v_exp_f32_e32 v106, v106
	s_nop 0
	v_add_f32_e32 v106, 1.0, v106
	v_rcp_f32_e32 v106, v106
	s_nop 0
	v_mul_f32_e32 v106, v111, v106
	v_mul_f32_e32 v105, v105, v106
	v_cvt_pk_bf16_f32 v104, v104, v105
	v_mul_f32_e32 v105, 0xbfb8aa3b, v112
	v_mul_f32_e32 v106, 0xbfb8aa3b, v113
	v_exp_f32_e32 v105, v105
	v_exp_f32_e32 v106, v106
	v_add_f32_e32 v105, 1.0, v105
	v_add_f32_e32 v106, 1.0, v106
	v_rcp_f32_e32 v105, v105
	v_rcp_f32_e32 v106, v106
	v_mul_f32_e32 v105, v112, v105
	v_mul_f32_e32 v106, v113, v106
	v_mul_f32_e32 v105, v124, v105
	v_mul_f32_e32 v106, v125, v106
	v_cvt_pk_bf16_f32 v105, v105, v106
	v_mad_i64_i32 v[106:107], s[12:13], v123, s55, v[120:121]
	v_lshl_add_u64 v[106:107], v[106:107], 0, v[118:119]
	global_store_dwordx4 v[106:107], v[102:105], off
	ds_read_b32 v102, v155 offset:128
	s_nop 0
	v_or_b32_e32 v103, 32, v156
	s_waitcnt lgkmcnt(0)
; __device__ __forceinline__ unsigned cvt_pk_bf16(float lo, float hi) { unsigned r; asm volatile("v_cvt_pk_bf16_f32 %0, %1, %2" : "=v"(r) : "v"(lo), "v"(hi)); return r; }
; #define LAS __attribute__((address_space(3)))
; __device__ __forceinline__ float sigmoid_f(float x) { return __builtin_amdgcn_rcpf(1.0f + __builtin_amdgcn_exp2f(-1.4426950408889634f * x)); }
; __device__ __forceinline__ float rstd4(const f32x4 q) { return __builtin_amdgcn_rsqf(((q[0] + q[1]) + (q[2] + q[3])) * (1.0f / DM) + EPS); }
;     __device__ __forceinline__ void operator()(const f32x4 (&acc)[2][2][4][2], const pg8::Unit& u, int wr, int wc, int fr, int fq, LAS unsigned char* lds, int wid, int lane, const pg8::Unit& nxt, bool has_next, int ui) const {
;     ...
;         for (int ai = 0; ai < 2; ++ai) {
; #pragma unroll
;             for (int m = 0; m < 4; ++m) {
;                 const int row = row0 + ai * 128 + m * 16; const float r_ = R[wr * 64 + fr + ai * 128 + m * 16];
;                 const f32x4 g0 = acc[ai][0][m][0] * r_, g1 = acc[ai][0][m][1] * r_, u0 = acc[ai][1][m][0] * r_, u1 = acc[ai][1][m][1] * r_;
;                 v4u w;
;                 w.x = cvt_pk_bf16(g0[0] * sigmoid_f(g0[0]) * u0[0], g0[1] * sigmoid_f(g0[1]) * u0[1]); w.y = cvt_pk_bf16(g0[2] * sigmoid_f(g0[2]) * u0[2], g0[3] * sigmoid_f(g0[3]) * u0[3]);
;                 w.z = cvt_pk_bf16(g1[0] * sigmoid_f(g1[0]) * u1[0], g1[1] * sigmoid_f(g1[1]) * u1[1]); w.w = cvt_pk_bf16(g1[2] * sigmoid_f(g1[2]) * u1[2], g1[3] * sigmoid_f(g1[3]) * u1[3]);
;                 *(v4u*)(ACT + (size_t)row * FF + col) = w;
;             }
;             if (ai == 0) {
;                 __builtin_amdgcn_sched_barrier(0);
;                 float rn = rstd4(qn); asm volatile("" : "+v"(rn));
;                 if (pre) ((LAS float*)(lds + RS_OFF))[((ui + 1) & 1) * 256 + tid] = rn;
	v_pk_mul_f32 v[94:95], v[94:95], v[102:103] op_sel_hi:[1,0]
	v_pk_mul_f32 v[104:105], v[84:85], v[102:103] op_sel_hi:[1,0]
	v_pk_mul_f32 v[84:85], v[82:83], v[102:103] op_sel_hi:[1,0]
	v_mul_f32_e32 v82, 0xbfb8aa3b, v94
	v_mul_f32_e32 v83, 0xbfb8aa3b, v95
	v_exp_f32_e32 v82, v82
	v_exp_f32_e32 v83, v83
	v_pk_mul_f32 v[86:87], v[86:87], v[102:103] op_sel_hi:[1,0]
	v_pk_mul_f32 v[96:97], v[96:97], v[102:103] op_sel_hi:[1,0]
	v_add_f32_e32 v82, 1.0, v82
	v_add_f32_e32 v83, 1.0, v83
	v_rcp_f32_e32 v82, v82
	v_rcp_f32_e32 v83, v83
	v_pk_mul_f32 v[88:89], v[88:89], v[102:103] op_sel_hi:[1,0]
	v_pk_mul_f32 v[90:91], v[90:91], v[102:103] op_sel_hi:[1,0]
	v_mul_f32_e32 v82, v94, v82
	v_mul_f32_e32 v83, v95, v83
	v_mul_f32_e32 v82, v86, v82
	v_mul_f32_e32 v83, v87, v83
	v_cvt_pk_bf16_f32 v82, v82, v83
	v_mul_f32_e32 v83, 0xbfb8aa3b, v96
	v_mul_f32_e32 v86, 0xbfb8aa3b, v97
	v_exp_f32_e32 v83, v83
	v_exp_f32_e32 v86, v86
	v_pk_mul_f32 v[92:93], v[92:93], v[102:103] op_sel_hi:[1,0]
	v_add_f32_e32 v83, 1.0, v83
	v_add_f32_e32 v86, 1.0, v86
	v_rcp_f32_e32 v83, v83
	v_rcp_f32_e32 v86, v86
	v_mul_f32_e32 v83, v96, v83
	v_mul_f32_e32 v86, v97, v86
	v_mul_f32_e32 v83, v88, v83
	v_mul_f32_e32 v86, v89, v86
	v_cvt_pk_bf16_f32 v83, v83, v86
	v_mul_f32_e32 v86, 0xbfb8aa3b, v90
	v_exp_f32_e32 v86, v86
	s_nop 0
	v_add_f32_e32 v86, 1.0, v86
	v_rcp_f32_e32 v86, v86
	s_nop 0
	v_mul_f32_e32 v86, v90, v86
	v_mul_f32_e32 v84, v84, v86
	v_mul_f32_e32 v86, 0xbfb8aa3b, v91
	v_exp_f32_e32 v86, v86
	s_nop 0
	v_add_f32_e32 v86, 1.0, v86
	v_rcp_f32_e32 v86, v86
	s_nop 0
	v_mul_f32_e32 v86, v91, v86
	v_mul_f32_e32 v85, v85, v86
	v_cvt_pk_bf16_f32 v84, v84, v85
	v_mul_f32_e32 v85, 0xbfb8aa3b, v92
	v_mul_f32_e32 v86, 0xbfb8aa3b, v93
	v_exp_f32_e32 v85, v85
	v_exp_f32_e32 v86, v86
	v_add_f32_e32 v85, 1.0, v85
	v_add_f32_e32 v86, 1.0, v86
	v_rcp_f32_e32 v85, v85
	v_rcp_f32_e32 v86, v86
	v_mul_f32_e32 v85, v92, v85
	v_mul_f32_e32 v86, v93, v86
	v_mul_f32_e32 v85, v104, v85
	v_mul_f32_e32 v86, v105, v86
	v_cvt_pk_bf16_f32 v85, v85, v86
	v_mad_i64_i32 v[86:87], s[12:13], v103, s55, v[120:121]
	v_lshl_add_u64 v[86:87], v[86:87], 0, v[118:119]
	global_store_dwordx4 v[86:87], v[82:85], off
	ds_read_b32 v82, v155 offset:192
	s_nop 0
	v_or_b32_e32 v83, 48, v156
	s_waitcnt lgkmcnt(0)
	v_pk_mul_f32 v[78:79], v[78:79], v[82:83] op_sel_hi:[1,0]
	v_pk_mul_f32 v[84:85], v[68:69], v[82:83] op_sel_hi:[1,0]
	v_pk_mul_f32 v[68:69], v[66:67], v[82:83] op_sel_hi:[1,0]
	v_mul_f32_e32 v66, 0xbfb8aa3b, v78
	v_mul_f32_e32 v67, 0xbfb8aa3b, v79
	v_exp_f32_e32 v66, v66
	v_exp_f32_e32 v67, v67
	v_pk_mul_f32 v[70:71], v[70:71], v[82:83] op_sel_hi:[1,0]
	v_pk_mul_f32 v[80:81], v[80:81], v[82:83] op_sel_hi:[1,0]
	v_add_f32_e32 v66, 1.0, v66
	v_add_f32_e32 v67, 1.0, v67
	v_rcp_f32_e32 v66, v66
	v_rcp_f32_e32 v67, v67
	v_pk_mul_f32 v[72:73], v[72:73], v[82:83] op_sel_hi:[1,0]
	v_pk_mul_f32 v[74:75], v[74:75], v[82:83] op_sel_hi:[1,0]
	v_mul_f32_e32 v66, v78, v66
	v_mul_f32_e32 v67, v79, v67
	v_mul_f32_e32 v66, v70, v66
	v_mul_f32_e32 v67, v71, v67
	v_cvt_pk_bf16_f32 v66, v66, v67
	v_mul_f32_e32 v67, 0xbfb8aa3b, v80
	v_mul_f32_e32 v70, 0xbfb8aa3b, v81
	v_exp_f32_e32 v67, v67
	v_exp_f32_e32 v70, v70
	v_pk_mul_f32 v[76:77], v[76:77], v[82:83] op_sel_hi:[1,0]
	v_add_f32_e32 v67, 1.0, v67
	v_add_f32_e32 v70, 1.0, v70
	v_rcp_f32_e32 v67, v67
	v_rcp_f32_e32 v70, v70
	v_mul_f32_e32 v67, v80, v67
	v_mul_f32_e32 v70, v81, v70
	v_mul_f32_e32 v67, v72, v67
	v_mul_f32_e32 v70, v73, v70
	v_cvt_pk_bf16_f32 v67, v67, v70
	v_mul_f32_e32 v70, 0xbfb8aa3b, v74
	v_exp_f32_e32 v70, v70
	s_nop 0
	v_add_f32_e32 v70, 1.0, v70
	v_rcp_f32_e32 v70, v70
	s_nop 0
	v_mul_f32_e32 v70, v74, v70
	v_mul_f32_e32 v68, v68, v70
	v_mul_f32_e32 v70, 0xbfb8aa3b, v75
	v_exp_f32_e32 v70, v70
	s_nop 0
	v_add_f32_e32 v70, 1.0, v70
	v_rcp_f32_e32 v70, v70
	s_nop 0
	v_mul_f32_e32 v70, v75, v70
	v_mul_f32_e32 v69, v69, v70
	v_cvt_pk_bf16_f32 v68, v68, v69
	v_mul_f32_e32 v69, 0xbfb8aa3b, v76
	v_mul_f32_e32 v70, 0xbfb8aa3b, v77
	v_exp_f32_e32 v69, v69
	v_exp_f32_e32 v70, v70
	v_add_f32_e32 v69, 1.0, v69
	v_add_f32_e32 v70, 1.0, v70
	v_rcp_f32_e32 v69, v69
	v_rcp_f32_e32 v70, v70
	v_mul_f32_e32 v69, v76, v69
	v_mul_f32_e32 v70, v77, v70
	v_mul_f32_e32 v69, v84, v69
	v_mul_f32_e32 v70, v85, v70
	v_cvt_pk_bf16_f32 v69, v69, v70
	v_mad_i64_i32 v[70:71], s[12:13], v83, s55, v[120:121]
	v_lshl_add_u64 v[70:71], v[70:71], 0, v[118:119]
	global_store_dwordx4 v[70:71], v[66:69], off
	s_waitcnt vmcnt(4)
	s_nop 0
	v_add_f32_e32 v66, v98, v99
	v_add_f32_e32 v67, v100, v101
	v_add_f32_e32 v66, v66, v67
	v_fmamk_f32 v66, v66, 0x3a800000, v245
	v_rsq_f32_e32 v66, v66
	s_and_saveexec_b64 s[22:23], s[20:21]
	s_xor_b32 s11, s11, 0x100
	v_lshl_add_u32 v67, s11, 2, v152
	ds_write_b32 v67, v66
	s_or_b64 exec, exec, s[22:23]
	ds_read_b32 v66, v155 offset:512
	v_add_u32_e32 v67, 0x80, v156
	s_mov_b64 s[20:21], -1
	s_cmp_eq_u32 s82, 21
	s_waitcnt lgkmcnt(0)
; __device__ __forceinline__ unsigned cvt_pk_bf16(float lo, float hi) { unsigned r; asm volatile("v_cvt_pk_bf16_f32 %0, %1, %2" : "=v"(r) : "v"(lo), "v"(hi)); return r; }
; __device__ __forceinline__ float sigmoid_f(float x) { return __builtin_amdgcn_rcpf(1.0f + __builtin_amdgcn_exp2f(-1.4426950408889634f * x)); }
;     __device__ __forceinline__ void operator()(const f32x4 (&acc)[2][2][4][2], const pg8::Unit& u, int wr, int wc, int fr, int fq, LAS unsigned char* lds, int wid, int lane, const pg8::Unit& nxt, bool has_next, int ui) const {
;     ...
;             for (int m = 0; m < 4; ++m) {
;                 const int row = row0 + ai * 128 + m * 16; const float r_ = R[wr * 64 + fr + ai * 128 + m * 16];
;                 const f32x4 g0 = acc[ai][0][m][0] * r_, g1 = acc[ai][0][m][1] * r_, u0 = acc[ai][1][m][0] * r_, u1 = acc[ai][1][m][1] * r_;
;                 v4u w;
;                 w.x = cvt_pk_bf16(g0[0] * sigmoid_f(g0[0]) * u0[0], g0[1] * sigmoid_f(g0[1]) * u0[1]); w.y = cvt_pk_bf16(g0[2] * sigmoid_f(g0[2]) * u0[2], g0[3] * sigmoid_f(g0[3]) * u0[3]);
;                 w.z = cvt_pk_bf16(g1[0] * sigmoid_f(g1[0]) * u1[0], g1[1] * sigmoid_f(g1[1]) * u1[1]); w.w = cvt_pk_bf16(g1[2] * sigmoid_f(g1[2]) * u1[2], g1[3] * sigmoid_f(g1[3]) * u1[3]);
;                 *(v4u*)(ACT + (size_t)row * FF + col) = w;
	v_pk_mul_f32 v[62:63], v[62:63], v[66:67] op_sel_hi:[1,0]
	v_pk_mul_f32 v[68:69], v[52:53], v[66:67] op_sel_hi:[1,0]
	v_mul_f32_e32 v52, 0xbfb8aa3b, v62
	v_mul_f32_e32 v53, 0xbfb8aa3b, v63
	v_exp_f32_e32 v52, v52
	v_exp_f32_e32 v53, v53
	v_pk_mul_f32 v[54:55], v[54:55], v[66:67] op_sel_hi:[1,0]
	v_pk_mul_f32 v[64:65], v[64:65], v[66:67] op_sel_hi:[1,0]
	v_add_f32_e32 v52, 1.0, v52
	v_add_f32_e32 v53, 1.0, v53
	v_rcp_f32_e32 v52, v52
	v_rcp_f32_e32 v53, v53
	v_pk_mul_f32 v[56:57], v[56:57], v[66:67] op_sel_hi:[1,0]
	v_pk_mul_f32 v[58:59], v[58:59], v[66:67] op_sel_hi:[1,0]
	v_mul_f32_e32 v52, v62, v52
	v_mul_f32_e32 v53, v63, v53
	v_mul_f32_e32 v52, v54, v52
	v_mul_f32_e32 v53, v55, v53
	v_cvt_pk_bf16_f32 v52, v52, v53
	v_mul_f32_e32 v53, 0xbfb8aa3b, v64
	v_mul_f32_e32 v54, 0xbfb8aa3b, v65
	v_exp_f32_e32 v53, v53
	v_exp_f32_e32 v54, v54
	v_pk_mul_f32 v[50:51], v[50:51], v[66:67] op_sel_hi:[1,0]
	v_pk_mul_f32 v[60:61], v[60:61], v[66:67] op_sel_hi:[1,0]
	v_add_f32_e32 v53, 1.0, v53
	v_add_f32_e32 v54, 1.0, v54
	v_rcp_f32_e32 v53, v53
	v_rcp_f32_e32 v54, v54
	v_mul_f32_e32 v53, v64, v53
	v_mul_f32_e32 v54, v65, v54
	v_mul_f32_e32 v53, v56, v53
	v_mul_f32_e32 v54, v57, v54
	v_cvt_pk_bf16_f32 v53, v53, v54
	v_mul_f32_e32 v54, 0xbfb8aa3b, v58
	v_exp_f32_e32 v54, v54
	s_nop 0
	v_add_f32_e32 v54, 1.0, v54
	v_rcp_f32_e32 v54, v54
	s_nop 0
	v_mul_f32_e32 v54, v58, v54
	v_mul_f32_e32 v50, v50, v54
	v_mul_f32_e32 v54, 0xbfb8aa3b, v59
	v_exp_f32_e32 v54, v54
	s_nop 0
	v_add_f32_e32 v54, 1.0, v54
	v_rcp_f32_e32 v54, v54
	s_nop 0
	v_mul_f32_e32 v54, v59, v54
	v_mul_f32_e32 v51, v51, v54
	v_cvt_pk_bf16_f32 v54, v50, v51
	v_mul_f32_e32 v50, 0xbfb8aa3b, v60
	v_mul_f32_e32 v51, 0xbfb8aa3b, v61
	v_exp_f32_e32 v50, v50
	v_exp_f32_e32 v51, v51
	v_add_f32_e32 v50, 1.0, v50
	v_add_f32_e32 v51, 1.0, v51
	v_rcp_f32_e32 v50, v50
	v_rcp_f32_e32 v51, v51
	v_mul_f32_e32 v50, v60, v50
	v_mul_f32_e32 v51, v61, v51
	v_mul_f32_e32 v50, v68, v50
	v_mul_f32_e32 v51, v69, v51
	v_cvt_pk_bf16_f32 v55, v50, v51
	v_mov_b64_e32 v[50:51], s[40:41]
	v_mad_i64_i32 v[56:57], s[12:13], v67, s55, v[50:51]
	v_lshl_add_u64 v[56:57], v[56:57], 0, v[118:119]
	global_store_dwordx4 v[56:57], v[52:55], off
	ds_read_b32 v52, v155 offset:576
	s_nop 0
	v_add_u32_e32 v53, 0x90, v156
	s_waitcnt lgkmcnt(0)
	v_pk_mul_f32 v[46:47], v[46:47], v[52:53] op_sel_hi:[1,0]
	v_pk_mul_f32 v[54:55], v[36:37], v[52:53] op_sel_hi:[1,0]
	v_pk_mul_f32 v[36:37], v[34:35], v[52:53] op_sel_hi:[1,0]
	v_mul_f32_e32 v34, 0xbfb8aa3b, v46
	v_mul_f32_e32 v35, 0xbfb8aa3b, v47
	v_exp_f32_e32 v34, v34
	v_exp_f32_e32 v35, v35
	v_pk_mul_f32 v[38:39], v[38:39], v[52:53] op_sel_hi:[1,0]
	v_pk_mul_f32 v[48:49], v[48:49], v[52:53] op_sel_hi:[1,0]
	v_add_f32_e32 v34, 1.0, v34
	v_add_f32_e32 v35, 1.0, v35
	v_rcp_f32_e32 v34, v34
	v_rcp_f32_e32 v35, v35
	v_pk_mul_f32 v[40:41], v[40:41], v[52:53] op_sel_hi:[1,0]
	v_pk_mul_f32 v[42:43], v[42:43], v[52:53] op_sel_hi:[1,0]
	v_mul_f32_e32 v34, v46, v34
	v_mul_f32_e32 v35, v47, v35
	v_mul_f32_e32 v34, v38, v34
	v_mul_f32_e32 v35, v39, v35
	v_cvt_pk_bf16_f32 v34, v34, v35
	v_mul_f32_e32 v35, 0xbfb8aa3b, v48
	v_mul_f32_e32 v38, 0xbfb8aa3b, v49
	v_exp_f32_e32 v35, v35
	v_exp_f32_e32 v38, v38
	v_pk_mul_f32 v[44:45], v[44:45], v[52:53] op_sel_hi:[1,0]
	v_add_f32_e32 v35, 1.0, v35
	v_add_f32_e32 v38, 1.0, v38
	v_rcp_f32_e32 v35, v35
	v_rcp_f32_e32 v38, v38
	v_mul_f32_e32 v35, v48, v35
	v_mul_f32_e32 v38, v49, v38
	v_mul_f32_e32 v35, v40, v35
	v_mul_f32_e32 v38, v41, v38
	v_cvt_pk_bf16_f32 v35, v35, v38
	v_mul_f32_e32 v38, 0xbfb8aa3b, v42
	v_exp_f32_e32 v38, v38
	s_nop 0
	v_add_f32_e32 v38, 1.0, v38
	v_rcp_f32_e32 v38, v38
	s_nop 0
	v_mul_f32_e32 v38, v42, v38
	v_mul_f32_e32 v36, v36, v38
	v_mul_f32_e32 v38, 0xbfb8aa3b, v43
	v_exp_f32_e32 v38, v38
	s_nop 0
	v_add_f32_e32 v38, 1.0, v38
	v_rcp_f32_e32 v38, v38
	s_nop 0
	v_mul_f32_e32 v38, v43, v38
	v_mul_f32_e32 v37, v37, v38
	v_cvt_pk_bf16_f32 v36, v36, v37
	v_mul_f32_e32 v37, 0xbfb8aa3b, v44
	v_mul_f32_e32 v38, 0xbfb8aa3b, v45
	v_exp_f32_e32 v37, v37
	v_exp_f32_e32 v38, v38
	v_add_f32_e32 v37, 1.0, v37
	v_add_f32_e32 v38, 1.0, v38
	v_rcp_f32_e32 v37, v37
	v_rcp_f32_e32 v38, v38
	v_mul_f32_e32 v37, v44, v37
	v_mul_f32_e32 v38, v45, v38
	v_mul_f32_e32 v37, v54, v37
	v_mul_f32_e32 v38, v55, v38
	v_cvt_pk_bf16_f32 v37, v37, v38
	v_mad_i64_i32 v[38:39], s[12:13], v53, s55, v[50:51]
	v_lshl_add_u64 v[38:39], v[38:39], 0, v[118:119]
	global_store_dwordx4 v[38:39], v[34:37], off
	ds_read_b32 v34, v155 offset:640
	s_nop 0
	v_add_u32_e32 v35, 0xa0, v156
	s_waitcnt lgkmcnt(0)
; __device__ __forceinline__ unsigned cvt_pk_bf16(float lo, float hi) { unsigned r; asm volatile("v_cvt_pk_bf16_f32 %0, %1, %2" : "=v"(r) : "v"(lo), "v"(hi)); return r; }
; #define PG8_BAR __builtin_amdgcn_s_barrier()
; __device__ __forceinline__ float sigmoid_f(float x) { return __builtin_amdgcn_rcpf(1.0f + __builtin_amdgcn_exp2f(-1.4426950408889634f * x)); }
; template <class Epi, class Sched>
; __device__ __forceinline__ void gemm_phase(PG8_LAS unsigned char* lds, const Gemm g, const Sched& S, const Epi& E) {
;     ...
;         if (!has_next) break;
; #pragma unroll
;         for (int a = 0; a < 2; ++a)
; #pragma unroll
;             for (int b = 0; b < 2; ++b)
; #pragma unroll
;                 for (int m = 0; m < 4; ++m)
; #pragma unroll
;                     for (int n = 0; n < 2; ++n) acc[a][b][m][n] = (f32x4){0.f, 0.f, 0.f, 0.f};
;         cur = nxt; cA = nA; cB = nB; ++ui;
;         if (wr == 1) PG8_BAR;
;     __device__ __forceinline__ void operator()(const f32x4 (&acc)[2][2][4][2], const pg8::Unit& u, int wr, int wc, int fr, int fq, LAS unsigned char* lds, int wid, int lane, const pg8::Unit& nxt, bool has_next, int ui) const {
;     ...
;             for (int m = 0; m < 4; ++m) {
;                 const int row = row0 + ai * 128 + m * 16; const float r_ = R[wr * 64 + fr + ai * 128 + m * 16];
;                 const f32x4 g0 = acc[ai][0][m][0] * r_, g1 = acc[ai][0][m][1] * r_, u0 = acc[ai][1][m][0] * r_, u1 = acc[ai][1][m][1] * r_;
;                 v4u w;
;                 w.x = cvt_pk_bf16(g0[0] * sigmoid_f(g0[0]) * u0[0], g0[1] * sigmoid_f(g0[1]) * u0[1]); w.y = cvt_pk_bf16(g0[2] * sigmoid_f(g0[2]) * u0[2], g0[3] * sigmoid_f(g0[3]) * u0[3]);
;                 w.z = cvt_pk_bf16(g1[0] * sigmoid_f(g1[0]) * u1[0], g1[1] * sigmoid_f(g1[1]) * u1[1]); w.w = cvt_pk_bf16(g1[2] * sigmoid_f(g1[2]) * u1[2], g1[3] * sigmoid_f(g1[3]) * u1[3]);
;                 *(v4u*)(ACT + (size_t)row * FF + col) = w;
	v_pk_mul_f32 v[30:31], v[30:31], v[34:35] op_sel_hi:[1,0]
	v_pk_mul_f32 v[36:37], v[20:21], v[34:35] op_sel_hi:[1,0]
	v_pk_mul_f32 v[20:21], v[18:19], v[34:35] op_sel_hi:[1,0]
	v_mul_f32_e32 v18, 0xbfb8aa3b, v30
	v_mul_f32_e32 v19, 0xbfb8aa3b, v31
	v_exp_f32_e32 v18, v18
	v_exp_f32_e32 v19, v19
	v_pk_mul_f32 v[22:23], v[22:23], v[34:35] op_sel_hi:[1,0]
	v_pk_mul_f32 v[32:33], v[32:33], v[34:35] op_sel_hi:[1,0]
	v_add_f32_e32 v18, 1.0, v18
	v_add_f32_e32 v19, 1.0, v19
	v_rcp_f32_e32 v18, v18
	v_rcp_f32_e32 v19, v19
	v_pk_mul_f32 v[24:25], v[24:25], v[34:35] op_sel_hi:[1,0]
	v_pk_mul_f32 v[26:27], v[26:27], v[34:35] op_sel_hi:[1,0]
	v_mul_f32_e32 v18, v30, v18
	v_mul_f32_e32 v19, v31, v19
	v_mul_f32_e32 v18, v22, v18
	v_mul_f32_e32 v19, v23, v19
	v_cvt_pk_bf16_f32 v18, v18, v19
	v_mul_f32_e32 v19, 0xbfb8aa3b, v32
	v_mul_f32_e32 v22, 0xbfb8aa3b, v33
	v_exp_f32_e32 v19, v19
	v_exp_f32_e32 v22, v22
	v_pk_mul_f32 v[28:29], v[28:29], v[34:35] op_sel_hi:[1,0]
	v_add_f32_e32 v19, 1.0, v19
	v_add_f32_e32 v22, 1.0, v22
	v_rcp_f32_e32 v19, v19
	v_rcp_f32_e32 v22, v22
	v_mul_f32_e32 v19, v32, v19
	v_mul_f32_e32 v22, v33, v22
	v_mul_f32_e32 v19, v24, v19
	v_mul_f32_e32 v22, v25, v22
	v_cvt_pk_bf16_f32 v19, v19, v22
	v_mul_f32_e32 v22, 0xbfb8aa3b, v26
	v_exp_f32_e32 v22, v22
	s_nop 0
	v_add_f32_e32 v22, 1.0, v22
	v_rcp_f32_e32 v22, v22
	s_nop 0
	v_mul_f32_e32 v22, v26, v22
	v_mul_f32_e32 v20, v20, v22
	v_mul_f32_e32 v22, 0xbfb8aa3b, v27
	v_exp_f32_e32 v22, v22
	s_nop 0
	v_add_f32_e32 v22, 1.0, v22
	v_rcp_f32_e32 v22, v22
	s_nop 0
	v_mul_f32_e32 v22, v27, v22
	v_mul_f32_e32 v21, v21, v22
	v_cvt_pk_bf16_f32 v20, v20, v21
	v_mul_f32_e32 v21, 0xbfb8aa3b, v28
	v_mul_f32_e32 v22, 0xbfb8aa3b, v29
	v_exp_f32_e32 v21, v21
	v_exp_f32_e32 v22, v22
	v_add_f32_e32 v21, 1.0, v21
	v_add_f32_e32 v22, 1.0, v22
	v_rcp_f32_e32 v21, v21
	v_rcp_f32_e32 v22, v22
	v_mul_f32_e32 v21, v28, v21
	v_mul_f32_e32 v22, v29, v22
	v_mul_f32_e32 v21, v36, v21
	v_mul_f32_e32 v22, v37, v22
	v_cvt_pk_bf16_f32 v21, v21, v22
	v_mad_i64_i32 v[22:23], s[12:13], v35, s55, v[50:51]
	v_lshl_add_u64 v[22:23], v[22:23], 0, v[118:119]
	global_store_dwordx4 v[22:23], v[18:21], off
	ds_read_b32 v18, v155 offset:704
	s_nop 0
	v_add_u32_e32 v19, 0xb0, v156
	s_waitcnt lgkmcnt(0)
	v_pk_mul_f32 v[14:15], v[14:15], v[18:19] op_sel_hi:[1,0]
	v_pk_mul_f32 v[20:21], v[4:5], v[18:19] op_sel_hi:[1,0]
	v_pk_mul_f32 v[4:5], v[2:3], v[18:19] op_sel_hi:[1,0]
	v_mul_f32_e32 v2, 0xbfb8aa3b, v14
	v_mul_f32_e32 v3, 0xbfb8aa3b, v15
	v_exp_f32_e32 v2, v2
	v_exp_f32_e32 v3, v3
	v_pk_mul_f32 v[6:7], v[6:7], v[18:19] op_sel_hi:[1,0]
	v_pk_mul_f32 v[16:17], v[16:17], v[18:19] op_sel_hi:[1,0]
	v_add_f32_e32 v2, 1.0, v2
	v_add_f32_e32 v3, 1.0, v3
	v_rcp_f32_e32 v2, v2
	v_rcp_f32_e32 v3, v3
	v_pk_mul_f32 v[8:9], v[8:9], v[18:19] op_sel_hi:[1,0]
	v_pk_mul_f32 v[10:11], v[10:11], v[18:19] op_sel_hi:[1,0]
	v_mul_f32_e32 v2, v14, v2
	v_mul_f32_e32 v3, v15, v3
	v_mul_f32_e32 v2, v6, v2
	v_mul_f32_e32 v3, v7, v3
	v_cvt_pk_bf16_f32 v2, v2, v3
	v_mul_f32_e32 v3, 0xbfb8aa3b, v16
	v_mul_f32_e32 v6, 0xbfb8aa3b, v17
	v_exp_f32_e32 v3, v3
	v_exp_f32_e32 v6, v6
	v_pk_mul_f32 v[12:13], v[12:13], v[18:19] op_sel_hi:[1,0]
	v_add_f32_e32 v3, 1.0, v3
	v_add_f32_e32 v6, 1.0, v6
	v_rcp_f32_e32 v3, v3
	v_rcp_f32_e32 v6, v6
	v_mul_f32_e32 v3, v16, v3
	v_mul_f32_e32 v6, v17, v6
	v_mul_f32_e32 v3, v8, v3
	v_mul_f32_e32 v6, v9, v6
	v_cvt_pk_bf16_f32 v3, v3, v6
	v_mul_f32_e32 v6, 0xbfb8aa3b, v10
	v_exp_f32_e32 v6, v6
	s_nop 0
	v_add_f32_e32 v6, 1.0, v6
	v_rcp_f32_e32 v6, v6
	s_nop 0
	v_mul_f32_e32 v6, v10, v6
	v_mul_f32_e32 v4, v4, v6
	v_mul_f32_e32 v6, 0xbfb8aa3b, v11
	v_exp_f32_e32 v6, v6
	s_nop 0
	v_add_f32_e32 v6, 1.0, v6
	v_rcp_f32_e32 v6, v6
	s_nop 0
	v_mul_f32_e32 v6, v11, v6
	v_mul_f32_e32 v5, v5, v6
	v_cvt_pk_bf16_f32 v4, v4, v5
	v_mul_f32_e32 v5, 0xbfb8aa3b, v12
	v_mul_f32_e32 v6, 0xbfb8aa3b, v13
	v_exp_f32_e32 v5, v5
	v_exp_f32_e32 v6, v6
	v_add_f32_e32 v5, 1.0, v5
	v_add_f32_e32 v6, 1.0, v6
	v_rcp_f32_e32 v5, v5
	v_rcp_f32_e32 v6, v6
	v_mul_f32_e32 v5, v12, v5
	v_mul_f32_e32 v6, v13, v6
	v_mul_f32_e32 v5, v20, v5
	v_mul_f32_e32 v6, v21, v6
	v_cvt_pk_bf16_f32 v5, v5, v6
	v_mad_i64_i32 v[6:7], s[12:13], v19, s55, v[50:51]
	v_lshl_add_u64 v[6:7], v[6:7], 0, v[118:119]
	global_store_dwordx4 v[6:7], v[2:5], off
	s_cbranch_scc1 .LBB0_574
	s_andn2_b64 vcc, exec, s[6:7]
	s_cbranch_vccnz .LBB0_573
	s_barrier
	s_branch .LBB0_573

; template <class Epi, class Sched>
; __device__ __forceinline__ void gemm_phase(PG8_LAS unsigned char* lds, const Gemm g, const Sched& S, const Epi& E) {
;     ...
; #pragma unroll
;     for (int a = 0; a < 2; ++a)
; #pragma unroll
;         for (int b = 0; b < 2; ++b)
; #pragma unroll
;             for (int m = 0; m < 4; ++m)
; #pragma unroll
;                 for (int n = 0; n < 2; ++n) acc[a][b][m][n] = (f32x4){0.f, 0.f, 0.f, 0.f};
;     ...
;         const bool has_next = S.next(ui + 1, nxt);
;         const char* nA = has_next ? (const char*)g.A + (size_t)nxt.pm * tstepA : cA; const char* nB = has_next ? (const char*)g.Bt + (size_t)nxt.pn * tstepB : cB;
;         for (int t = 0; t < nt; t += 2) {
;             const bool last = (t == nt - 2);
;             const char* a1 = cA + (size_t)(t + 1) * kstep;
;             const char* a2 = last ? nA : cA + (size_t)(t + 2) * kstep; const char* b2 = last ? nB : cB + (size_t)(t + 2) * kstep;
;             const char* a3 = a2 + kstep; const char* b3 = b2 + kstep;
.LBB0_666:
	s_add_u32 s19, s28, 0x100
	v_mov_b32_e32 v2, 0
	s_addc_u32 s25, s29, 0
	s_mov_b32 s33, -2
	v_mov_b32_e32 v3, v2
	v_mov_b64_e32 v[4:5], 0
	v_mov_b64_e32 v[6:7], 0
	v_mov_b64_e32 v[8:9], 0
	v_mov_b64_e32 v[18:19], 0
	v_mov_b64_e32 v[20:21], 0
	v_mov_b64_e32 v[22:23], 0
	v_mov_b64_e32 v[24:25], 0
	v_mov_b64_e32 v[34:35], 0
	v_mov_b64_e32 v[36:37], 0
	v_mov_b64_e32 v[38:39], 0
	v_mov_b64_e32 v[40:41], 0
	v_mov_b64_e32 v[50:51], 0
	v_mov_b64_e32 v[52:53], 0
	v_mov_b64_e32 v[54:55], 0
	v_mov_b64_e32 v[56:57], 0
	v_mov_b64_e32 v[10:11], 0
	v_mov_b64_e32 v[12:13], 0
	v_mov_b64_e32 v[14:15], 0
	v_mov_b64_e32 v[16:17], 0
	v_mov_b64_e32 v[26:27], 0
	v_mov_b64_e32 v[28:29], 0
	v_mov_b64_e32 v[30:31], 0
	v_mov_b64_e32 v[32:33], 0
	v_mov_b64_e32 v[42:43], 0
	v_mov_b64_e32 v[44:45], 0
	v_mov_b64_e32 v[46:47], 0
	v_mov_b64_e32 v[48:49], 0
	v_mov_b64_e32 v[58:59], 0
	v_mov_b64_e32 v[60:61], 0
	v_mov_b64_e32 v[62:63], 0
	v_mov_b64_e32 v[64:65], 0
	v_mov_b64_e32 v[66:67], 0
	v_mov_b64_e32 v[68:69], 0
	v_mov_b64_e32 v[70:71], 0
	v_mov_b64_e32 v[72:73], 0
	v_mov_b64_e32 v[82:83], 0
	v_mov_b64_e32 v[84:85], 0
	v_mov_b64_e32 v[86:87], 0
	v_mov_b64_e32 v[88:89], 0
	v_mov_b64_e32 v[114:115], 0
	v_mov_b64_e32 v[116:117], 0
	v_mov_b64_e32 v[118:119], 0
	v_mov_b64_e32 v[120:121], 0
	v_mov_b64_e32 v[130:131], 0
	v_mov_b64_e32 v[132:133], 0
	v_mov_b64_e32 v[134:135], 0
	v_mov_b64_e32 v[136:137], 0
	v_mov_b64_e32 v[74:75], 0
	v_mov_b64_e32 v[76:77], 0
	v_mov_b64_e32 v[78:79], 0
	v_mov_b64_e32 v[80:81], 0
	v_mov_b64_e32 v[102:103], 0
	v_mov_b64_e32 v[104:105], 0
	v_mov_b64_e32 v[110:111], 0
	v_mov_b64_e32 v[112:113], 0
	v_mov_b64_e32 v[122:123], 0
	v_mov_b64_e32 v[124:125], 0
	v_mov_b64_e32 v[126:127], 0
	v_mov_b64_e32 v[128:129], 0
	v_mov_b64_e32 v[138:139], 0
	v_mov_b64_e32 v[140:141], 0
	v_mov_b64_e32 v[142:143], 0
	v_mov_b64_e32 v[144:145], 0

; template <class Epi, class Sched>
; __device__ __forceinline__ void gemm_phase(PG8_LAS unsigned char* lds, const Gemm g, const Sched& S, const Epi& E) {
;     ...
; #pragma unroll
;     for (int a = 0; a < 2; ++a)
; #pragma unroll
;         for (int b = 0; b < 2; ++b)
; #pragma unroll
;             for (int m = 0; m < 4; ++m)
; #pragma unroll
;                 for (int n = 0; n < 2; ++n) acc[a][b][m][n] = (f32x4){0.f, 0.f, 0.f, 0.f};
;     ...
;         const bool has_next = S.next(ui + 1, nxt);
;         const char* nA = has_next ? (const char*)g.A + (size_t)nxt.pm * tstepA : cA; const char* nB = has_next ? (const char*)g.Bt + (size_t)nxt.pn * tstepB : cB;
;         for (int t = 0; t < nt; t += 2) {
;             const bool last = (t == nt - 2);
;             const char* a1 = cA + (size_t)(t + 1) * kstep;
;             const char* a2 = last ? nA : cA + (size_t)(t + 2) * kstep; const char* b2 = last ? nB : cB + (size_t)(t + 2) * kstep;
;             const char* a3 = a2 + kstep; const char* b3 = b2 + kstep;
.LBB0_732:
	s_add_u32 s19, s24, 0x100
	v_mov_b32_e32 v2, 0
	s_addc_u32 s21, s25, 0
	s_mov_b32 s33, -2
	v_mov_b32_e32 v3, v2
	v_mov_b32_e32 v4, v2
	v_mov_b32_e32 v5, v2
	v_mov_b32_e32 v6, v2
	v_mov_b32_e32 v7, v2
	v_mov_b32_e32 v8, v2
	v_mov_b32_e32 v9, v2
	s_waitcnt vmcnt(0)
	v_mov_b64_e32 v[34:35], 0
	v_mov_b64_e32 v[36:37], 0
	v_mov_b64_e32 v[38:39], 0
	v_mov_b64_e32 v[40:41], 0
	v_mov_b64_e32 v[50:51], 0
	v_mov_b64_e32 v[52:53], 0
	v_mov_b64_e32 v[54:55], 0
	v_mov_b64_e32 v[56:57], 0
	v_mov_b64_e32 v[66:67], 0
	v_mov_b64_e32 v[68:69], 0
	v_mov_b64_e32 v[70:71], 0
	v_mov_b64_e32 v[72:73], 0
	v_mov_b64_e32 v[10:11], 0
	v_mov_b64_e32 v[12:13], 0
	v_mov_b64_e32 v[14:15], 0
	v_mov_b64_e32 v[16:17], 0
	v_mov_b64_e32 v[42:43], 0
	v_mov_b64_e32 v[44:45], 0
	v_mov_b64_e32 v[46:47], 0
	v_mov_b64_e32 v[48:49], 0
	v_mov_b64_e32 v[58:59], 0
	v_mov_b64_e32 v[60:61], 0
	v_mov_b64_e32 v[62:63], 0
	v_mov_b64_e32 v[64:65], 0
	v_mov_b64_e32 v[74:75], 0
	v_mov_b64_e32 v[76:77], 0
	v_mov_b64_e32 v[78:79], 0
	v_mov_b64_e32 v[80:81], 0
	v_mov_b64_e32 v[82:83], 0
	v_mov_b64_e32 v[84:85], 0
	v_mov_b64_e32 v[86:87], 0
	v_mov_b64_e32 v[88:89], 0
	v_mov_b64_e32 v[98:99], 0
	v_mov_b64_e32 v[100:101], 0
	v_mov_b64_e32 v[102:103], 0
	v_mov_b64_e32 v[104:105], 0
	v_mov_b64_e32 v[114:115], 0
	v_mov_b64_e32 v[116:117], 0
	v_mov_b64_e32 v[118:119], 0
	v_mov_b64_e32 v[120:121], 0
	v_mov_b64_e32 v[130:131], 0
	v_mov_b64_e32 v[132:133], 0
	v_mov_b64_e32 v[134:135], 0
	v_mov_b64_e32 v[136:137], 0
	v_mov_b64_e32 v[90:91], 0
	v_mov_b64_e32 v[92:93], 0
	v_mov_b64_e32 v[94:95], 0
	v_mov_b64_e32 v[96:97], 0
	v_mov_b64_e32 v[106:107], 0
	v_mov_b64_e32 v[108:109], 0
	v_mov_b64_e32 v[110:111], 0
	v_mov_b64_e32 v[112:113], 0
	v_mov_b64_e32 v[122:123], 0
	v_mov_b64_e32 v[124:125], 0
	v_mov_b64_e32 v[126:127], 0
	v_mov_b64_e32 v[128:129], 0
	v_mov_b64_e32 v[142:143], 0
	v_mov_b64_e32 v[144:145], 0
	v_mov_b64_e32 v[146:147], 0
	v_mov_b64_e32 v[148:149], 0
